# P8 epilogue rewritten by hand (no register shuffles, row stats preloaded at tile start), on top of R1 staging-time decay and write-through ACT
# speedup vs baseline: 1.0175x; 1.0030x over previous
.LBB0_1336:
	s_ashr_i32 s15, s14, 31
	s_lshl_b64 s[16:17], s[14:15], 19
	s_add_u32 s16, s22, s16
	s_addc_u32 s17, s23, s17
	s_and_b64 s[34:35], s[4:5], exec
	s_cselect_b32 s15, s17, s41
	s_cselect_b32 s19, s16, s40
	s_ashr_i32 s13, s12, 31
	s_lshl_b64 s[34:35], s[12:13], 19
	s_add_u32 s36, s3, s34
	s_addc_u32 s37, s20, s35
	s_and_b64 s[34:35], s[4:5], exec
	s_cselect_b32 s13, s37, s43
	s_cselect_b32 s62, s36, s42
	s_add_u32 s40, s40, 0x40080
	s_addc_u32 s41, s41, 0
	s_add_u32 s63, s42, 0x100
	v_mov_b32_e32 v0, 0
	s_addc_u32 s64, s43, 0
	s_mov_b32 s65, -2
	s_lshl_b32 s92, s38, 8
	s_add_i32 s92, s92, s53
	v_or_b32_e32 v228, s92, v148
	v_ashrrev_i32_e32 v229, 31, v228
	v_lshl_add_u64 v[228:229], v[228:229], 2, s[0:1]
	global_load_dword v240, v[228:229], off
	global_load_dword v241, v[228:229], off offset:64
	global_load_dword v242, v[228:229], off offset:128
	global_load_dword v243, v[228:229], off offset:192
	global_load_dword v244, v[228:229], off offset:512
	global_load_dword v245, v[228:229], off offset:576
	global_load_dword v246, v[228:229], off offset:640
	global_load_dword v247, v[228:229], off offset:704
	v_mov_b32_e32 v1, v0
	v_mov_b32_e32 v2, v0
	v_mov_b32_e32 v3, v0
	v_mov_b32_e32 v8, v0
	v_mov_b32_e32 v9, v0
	v_mov_b32_e32 v10, v0
	v_mov_b32_e32 v11, v0
	v_mov_b32_e32 v16, v0
	v_mov_b32_e32 v17, v0
	v_mov_b32_e32 v18, v0
	v_mov_b32_e32 v19, v0
	v_mov_b32_e32 v24, v0
	v_mov_b32_e32 v25, v0
	v_mov_b32_e32 v26, v0
	v_mov_b32_e32 v27, v0
	v_mov_b32_e32 v32, v0
	v_mov_b32_e32 v33, v0
	v_mov_b32_e32 v34, v0
	v_mov_b32_e32 v35, v0
	v_mov_b32_e32 v40, v0
	v_mov_b32_e32 v41, v0
	v_mov_b32_e32 v42, v0
	v_mov_b32_e32 v43, v0
	v_mov_b32_e32 v48, v0
	v_mov_b32_e32 v49, v0
	v_mov_b32_e32 v50, v0
	v_mov_b32_e32 v51, v0
	v_mov_b32_e32 v56, v0
	v_mov_b32_e32 v57, v0
	v_mov_b32_e32 v58, v0
	v_mov_b32_e32 v59, v0
	v_mov_b32_e32 v4, v0
	v_mov_b32_e32 v5, v0
	v_mov_b32_e32 v6, v0
	v_mov_b32_e32 v7, v0
	v_mov_b32_e32 v12, v0
	v_mov_b32_e32 v13, v0
	v_mov_b32_e32 v14, v0
	v_mov_b32_e32 v15, v0
	v_mov_b32_e32 v20, v0
	v_mov_b32_e32 v21, v0
	v_mov_b32_e32 v22, v0
	v_mov_b32_e32 v23, v0
	v_mov_b32_e32 v28, v0
	v_mov_b32_e32 v29, v0
	v_mov_b32_e32 v30, v0
	v_mov_b32_e32 v31, v0
	v_mov_b32_e32 v36, v0
	v_mov_b32_e32 v37, v0
	v_mov_b32_e32 v38, v0
	v_mov_b32_e32 v39, v0
	v_mov_b32_e32 v44, v0
	v_mov_b32_e32 v45, v0
	v_mov_b32_e32 v46, v0
	v_mov_b32_e32 v47, v0
	v_mov_b32_e32 v52, v0
	v_mov_b32_e32 v53, v0
	v_mov_b32_e32 v54, v0
	v_mov_b32_e32 v55, v0
	v_mov_b32_e32 v60, v0
	v_mov_b32_e32 v61, v0
	v_mov_b32_e32 v62, v0
	v_mov_b32_e32 v63, v0
	v_mov_b32_e32 v64, v0
	v_mov_b32_e32 v65, v0
	v_mov_b32_e32 v66, v0
	v_mov_b32_e32 v67, v0
	v_mov_b32_e32 v72, v0
	v_mov_b32_e32 v73, v0
	v_mov_b32_e32 v74, v0
	v_mov_b32_e32 v75, v0
	v_mov_b32_e32 v80, v0
	v_mov_b32_e32 v81, v0
	v_mov_b32_e32 v82, v0
	v_mov_b32_e32 v83, v0
	v_mov_b32_e32 v88, v0
	v_mov_b32_e32 v89, v0
	v_mov_b32_e32 v90, v0
	v_mov_b32_e32 v91, v0
	v_mov_b32_e32 v96, v0
	v_mov_b32_e32 v97, v0
	v_mov_b32_e32 v98, v0
	v_mov_b32_e32 v99, v0
	v_mov_b32_e32 v104, v0
	v_mov_b32_e32 v105, v0
	v_mov_b32_e32 v106, v0
	v_mov_b32_e32 v107, v0
	v_mov_b32_e32 v120, v0
	v_mov_b32_e32 v121, v0
	v_mov_b32_e32 v122, v0
	v_mov_b32_e32 v123, v0
	v_mov_b32_e32 v124, v0
	v_mov_b32_e32 v125, v0
	v_mov_b32_e32 v126, v0
	v_mov_b32_e32 v127, v0
	v_mov_b32_e32 v68, v0
	v_mov_b32_e32 v69, v0
	v_mov_b32_e32 v70, v0
	v_mov_b32_e32 v71, v0
	v_mov_b32_e32 v76, v0
	v_mov_b32_e32 v77, v0
	v_mov_b32_e32 v78, v0
	v_mov_b32_e32 v79, v0
	v_mov_b32_e32 v84, v0
	v_mov_b32_e32 v85, v0
	v_mov_b32_e32 v86, v0
	v_mov_b32_e32 v87, v0
	v_mov_b32_e32 v92, v0
	v_mov_b32_e32 v93, v0
	v_mov_b32_e32 v94, v0
	v_mov_b32_e32 v95, v0
	v_mov_b32_e32 v100, v0
	v_mov_b32_e32 v101, v0
	v_mov_b32_e32 v102, v0
	v_mov_b32_e32 v103, v0
	v_mov_b32_e32 v108, v0
	v_mov_b32_e32 v109, v0
	v_mov_b32_e32 v110, v0
	v_mov_b32_e32 v111, v0
	v_mov_b32_e32 v112, v0
	v_mov_b32_e32 v113, v0
	v_mov_b32_e32 v114, v0
	v_mov_b32_e32 v115, v0
	v_mov_b32_e32 v116, v0
	v_mov_b32_e32 v117, v0
	v_mov_b32_e32 v118, v0
	v_mov_b32_e32 v119, v0

.LBB0_1340:
	s_lshl_b32 s13, s38, 8
	s_add_i32 s15, s13, s53
	v_or_b32_e32 v154, s15, v148
	s_lshl_b32 s13, s18, 7
	s_or_b32 s13, s13, s54
	s_ashr_i32 s15, s15, 8
	s_ashr_i32 s13, s13, 6
	s_mul_i32 s15, s15, 44
	s_add_i32 s18, s15, s13
	s_ashr_i32 s19, s18, 31
	s_lshl_b64 s[18:19], s[18:19], 15
	s_add_u32 s18, s46, s18
	s_addc_u32 s19, s47, s19
	v_lshlrev_b32_e32 v228, 7, v154
	v_and_b32_e32 v228, 0x6780, v228
	v_mov_b32_e32 v229, 0
	v_mov_b32_e32 v232, v146
	v_mov_b32_e32 v233, 0
	v_lshl_add_u64 v[228:229], s[18:19], 0, v[228:229]
	v_lshl_add_u64 v[228:229], v[228:229], 0, v[232:233]
	s_mov_b32 s93, 0
	s_mov_b32 s92, 0x1000
	v_lshl_add_u64 v[234:235], v[228:229], 0, s[92:93]
	s_mov_b32 s92, 0x4000
	v_lshl_add_u64 v[236:237], v[228:229], 0, s[92:93]
	s_mov_b32 s92, 0x5000
	v_lshl_add_u64 v[238:239], v[228:229], 0, s[92:93]
	s_mov_b32 s94, 0xbfb8aa3b
	s_mov_b32 s95, 0xbfb8aa3b
	v_fmamk_f32 v160, v240, 0x3a800000, v153
	v_fmamk_f32 v162, v241, 0x3a800000, v153
	v_fmamk_f32 v164, v242, 0x3a800000, v153
	v_fmamk_f32 v166, v243, 0x3a800000, v153
	v_fmamk_f32 v168, v244, 0x3a800000, v153
	v_fmamk_f32 v170, v245, 0x3a800000, v153
	v_fmamk_f32 v172, v246, 0x3a800000, v153
	v_fmamk_f32 v174, v247, 0x3a800000, v153
	v_rsq_f32_e32 v160, v160
	v_rsq_f32_e32 v162, v162
	v_rsq_f32_e32 v164, v164
	v_rsq_f32_e32 v166, v166
	v_rsq_f32_e32 v168, v168
	v_rsq_f32_e32 v170, v170
	v_rsq_f32_e32 v172, v172
	v_rsq_f32_e32 v174, v174
	v_pk_mul_f32 v[116:117], v[116:117], v[160:161] op_sel_hi:[1,0]
	v_pk_mul_f32 v[118:119], v[118:119], v[160:161] op_sel_hi:[1,0]
	v_pk_mul_f32 v[112:113], v[112:113], v[160:161] op_sel_hi:[1,0]
	v_pk_mul_f32 v[114:115], v[114:115], v[160:161] op_sel_hi:[1,0]
	v_pk_mul_f32 v[124:125], v[124:125], v[160:161] op_sel_hi:[1,0]
	v_pk_mul_f32 v[126:127], v[126:127], v[160:161] op_sel_hi:[1,0]
	v_pk_mul_f32 v[120:121], v[120:121], v[160:161] op_sel_hi:[1,0]
	v_pk_mul_f32 v[122:123], v[122:123], v[160:161] op_sel_hi:[1,0]
	v_pk_mul_f32 v[176:177], v[116:117], s[94:95]
	v_pk_mul_f32 v[178:179], v[118:119], s[94:95]
	v_pk_mul_f32 v[180:181], v[112:113], s[94:95]
	v_pk_mul_f32 v[182:183], v[114:115], s[94:95]
	v_exp_f32_e32 v176, v176
	v_exp_f32_e32 v177, v177
	v_exp_f32_e32 v178, v178
	v_exp_f32_e32 v179, v179
	v_exp_f32_e32 v180, v180
	v_exp_f32_e32 v181, v181
	v_exp_f32_e32 v182, v182
	v_exp_f32_e32 v183, v183
	v_pk_add_f32 v[176:177], v[176:177], 1.0 op_sel_hi:[1,0]
	v_pk_add_f32 v[178:179], v[178:179], 1.0 op_sel_hi:[1,0]
	v_pk_add_f32 v[180:181], v[180:181], 1.0 op_sel_hi:[1,0]
	v_pk_add_f32 v[182:183], v[182:183], 1.0 op_sel_hi:[1,0]
	v_rcp_f32_e32 v176, v176
	v_rcp_f32_e32 v177, v177
	v_rcp_f32_e32 v178, v178
	v_rcp_f32_e32 v179, v179
	v_rcp_f32_e32 v180, v180
	v_rcp_f32_e32 v181, v181
	v_rcp_f32_e32 v182, v182
	v_rcp_f32_e32 v183, v183
	v_pk_mul_f32 v[116:117], v[116:117], v[176:177]
	v_pk_mul_f32 v[118:119], v[118:119], v[178:179]
	v_pk_mul_f32 v[112:113], v[112:113], v[180:181]
	v_pk_mul_f32 v[114:115], v[114:115], v[182:183]
	v_pk_mul_f32 v[116:117], v[124:125], v[116:117]
	v_pk_mul_f32 v[118:119], v[126:127], v[118:119]
	v_pk_mul_f32 v[112:113], v[120:121], v[112:113]
	v_pk_mul_f32 v[114:115], v[122:123], v[114:115]
	v_cvt_pk_bf16_f32 v184, v116, v117
	v_cvt_pk_bf16_f32 v185, v118, v119
	v_cvt_pk_bf16_f32 v186, v112, v113
	v_cvt_pk_bf16_f32 v187, v114, v115
	global_store_dwordx4 v[228:229], v[184:187], off sc1
	v_pk_mul_f32 v[108:109], v[108:109], v[162:163] op_sel_hi:[1,0]
	v_pk_mul_f32 v[110:111], v[110:111], v[162:163] op_sel_hi:[1,0]
	v_pk_mul_f32 v[100:101], v[100:101], v[162:163] op_sel_hi:[1,0]
	v_pk_mul_f32 v[102:103], v[102:103], v[162:163] op_sel_hi:[1,0]
	v_pk_mul_f32 v[104:105], v[104:105], v[162:163] op_sel_hi:[1,0]
	v_pk_mul_f32 v[106:107], v[106:107], v[162:163] op_sel_hi:[1,0]
	v_pk_mul_f32 v[96:97], v[96:97], v[162:163] op_sel_hi:[1,0]
	v_pk_mul_f32 v[98:99], v[98:99], v[162:163] op_sel_hi:[1,0]
	v_pk_mul_f32 v[176:177], v[108:109], s[94:95]
	v_pk_mul_f32 v[178:179], v[110:111], s[94:95]
	v_pk_mul_f32 v[180:181], v[100:101], s[94:95]
	v_pk_mul_f32 v[182:183], v[102:103], s[94:95]
	v_exp_f32_e32 v176, v176
	v_exp_f32_e32 v177, v177
	v_exp_f32_e32 v178, v178
	v_exp_f32_e32 v179, v179
	v_exp_f32_e32 v180, v180
	v_exp_f32_e32 v181, v181
	v_exp_f32_e32 v182, v182
	v_exp_f32_e32 v183, v183
	v_pk_add_f32 v[176:177], v[176:177], 1.0 op_sel_hi:[1,0]
	v_pk_add_f32 v[178:179], v[178:179], 1.0 op_sel_hi:[1,0]
	v_pk_add_f32 v[180:181], v[180:181], 1.0 op_sel_hi:[1,0]
	v_pk_add_f32 v[182:183], v[182:183], 1.0 op_sel_hi:[1,0]
	v_rcp_f32_e32 v176, v176
	v_rcp_f32_e32 v177, v177
	v_rcp_f32_e32 v178, v178
	v_rcp_f32_e32 v179, v179
	v_rcp_f32_e32 v180, v180
	v_rcp_f32_e32 v181, v181
	v_rcp_f32_e32 v182, v182
	v_rcp_f32_e32 v183, v183
	v_pk_mul_f32 v[108:109], v[108:109], v[176:177]
	v_pk_mul_f32 v[110:111], v[110:111], v[178:179]
	v_pk_mul_f32 v[100:101], v[100:101], v[180:181]
	v_pk_mul_f32 v[102:103], v[102:103], v[182:183]
	v_pk_mul_f32 v[108:109], v[104:105], v[108:109]
	v_pk_mul_f32 v[110:111], v[106:107], v[110:111]
	v_pk_mul_f32 v[100:101], v[96:97], v[100:101]
	v_pk_mul_f32 v[102:103], v[98:99], v[102:103]
	v_cvt_pk_bf16_f32 v188, v108, v109
	v_cvt_pk_bf16_f32 v189, v110, v111
	v_cvt_pk_bf16_f32 v190, v100, v101
	v_cvt_pk_bf16_f32 v191, v102, v103
	global_store_dwordx4 v[228:229], v[188:191], off offset:2048 sc1
	v_pk_mul_f32 v[92:93], v[92:93], v[164:165] op_sel_hi:[1,0]
	v_pk_mul_f32 v[94:95], v[94:95], v[164:165] op_sel_hi:[1,0]
	v_pk_mul_f32 v[84:85], v[84:85], v[164:165] op_sel_hi:[1,0]
	v_pk_mul_f32 v[86:87], v[86:87], v[164:165] op_sel_hi:[1,0]
	v_pk_mul_f32 v[88:89], v[88:89], v[164:165] op_sel_hi:[1,0]
	v_pk_mul_f32 v[90:91], v[90:91], v[164:165] op_sel_hi:[1,0]
	v_pk_mul_f32 v[80:81], v[80:81], v[164:165] op_sel_hi:[1,0]
	v_pk_mul_f32 v[82:83], v[82:83], v[164:165] op_sel_hi:[1,0]
	v_pk_mul_f32 v[176:177], v[92:93], s[94:95]
	v_pk_mul_f32 v[178:179], v[94:95], s[94:95]
	v_pk_mul_f32 v[180:181], v[84:85], s[94:95]
	v_pk_mul_f32 v[182:183], v[86:87], s[94:95]
	v_exp_f32_e32 v176, v176
	v_exp_f32_e32 v177, v177
	v_exp_f32_e32 v178, v178
	v_exp_f32_e32 v179, v179
	v_exp_f32_e32 v180, v180
	v_exp_f32_e32 v181, v181
	v_exp_f32_e32 v182, v182
	v_exp_f32_e32 v183, v183
	v_pk_add_f32 v[176:177], v[176:177], 1.0 op_sel_hi:[1,0]
	v_pk_add_f32 v[178:179], v[178:179], 1.0 op_sel_hi:[1,0]
	v_pk_add_f32 v[180:181], v[180:181], 1.0 op_sel_hi:[1,0]
	v_pk_add_f32 v[182:183], v[182:183], 1.0 op_sel_hi:[1,0]
	v_rcp_f32_e32 v176, v176
	v_rcp_f32_e32 v177, v177
	v_rcp_f32_e32 v178, v178
	v_rcp_f32_e32 v179, v179
	v_rcp_f32_e32 v180, v180
	v_rcp_f32_e32 v181, v181
	v_rcp_f32_e32 v182, v182
	v_rcp_f32_e32 v183, v183
	v_pk_mul_f32 v[92:93], v[92:93], v[176:177]
	v_pk_mul_f32 v[94:95], v[94:95], v[178:179]
	v_pk_mul_f32 v[84:85], v[84:85], v[180:181]
	v_pk_mul_f32 v[86:87], v[86:87], v[182:183]
	v_pk_mul_f32 v[92:93], v[88:89], v[92:93]
	v_pk_mul_f32 v[94:95], v[90:91], v[94:95]
	v_pk_mul_f32 v[84:85], v[80:81], v[84:85]
	v_pk_mul_f32 v[86:87], v[82:83], v[86:87]
	v_cvt_pk_bf16_f32 v184, v92, v93
	v_cvt_pk_bf16_f32 v185, v94, v95
	v_cvt_pk_bf16_f32 v186, v84, v85
	v_cvt_pk_bf16_f32 v187, v86, v87
	global_store_dwordx4 v[234:235], v[184:187], off sc1
	v_pk_mul_f32 v[76:77], v[76:77], v[166:167] op_sel_hi:[1,0]
	v_pk_mul_f32 v[78:79], v[78:79], v[166:167] op_sel_hi:[1,0]
	v_pk_mul_f32 v[68:69], v[68:69], v[166:167] op_sel_hi:[1,0]
	v_pk_mul_f32 v[70:71], v[70:71], v[166:167] op_sel_hi:[1,0]
	v_pk_mul_f32 v[72:73], v[72:73], v[166:167] op_sel_hi:[1,0]
	v_pk_mul_f32 v[74:75], v[74:75], v[166:167] op_sel_hi:[1,0]
	v_pk_mul_f32 v[64:65], v[64:65], v[166:167] op_sel_hi:[1,0]
	v_pk_mul_f32 v[66:67], v[66:67], v[166:167] op_sel_hi:[1,0]
	v_pk_mul_f32 v[176:177], v[76:77], s[94:95]
	v_pk_mul_f32 v[178:179], v[78:79], s[94:95]
	v_pk_mul_f32 v[180:181], v[68:69], s[94:95]
	v_pk_mul_f32 v[182:183], v[70:71], s[94:95]
	v_exp_f32_e32 v176, v176
	v_exp_f32_e32 v177, v177
	v_exp_f32_e32 v178, v178
	v_exp_f32_e32 v179, v179
	v_exp_f32_e32 v180, v180
	v_exp_f32_e32 v181, v181
	v_exp_f32_e32 v182, v182
	v_exp_f32_e32 v183, v183
	v_pk_add_f32 v[176:177], v[176:177], 1.0 op_sel_hi:[1,0]
	v_pk_add_f32 v[178:179], v[178:179], 1.0 op_sel_hi:[1,0]
	v_pk_add_f32 v[180:181], v[180:181], 1.0 op_sel_hi:[1,0]
	v_pk_add_f32 v[182:183], v[182:183], 1.0 op_sel_hi:[1,0]
	v_rcp_f32_e32 v176, v176
	v_rcp_f32_e32 v177, v177
	v_rcp_f32_e32 v178, v178
	v_rcp_f32_e32 v179, v179
	v_rcp_f32_e32 v180, v180
	v_rcp_f32_e32 v181, v181
	v_rcp_f32_e32 v182, v182
	v_rcp_f32_e32 v183, v183
	v_pk_mul_f32 v[76:77], v[76:77], v[176:177]
	v_pk_mul_f32 v[78:79], v[78:79], v[178:179]
	v_pk_mul_f32 v[68:69], v[68:69], v[180:181]
	v_pk_mul_f32 v[70:71], v[70:71], v[182:183]
	v_pk_mul_f32 v[76:77], v[72:73], v[76:77]
	v_pk_mul_f32 v[78:79], v[74:75], v[78:79]
	v_pk_mul_f32 v[68:69], v[64:65], v[68:69]
	v_pk_mul_f32 v[70:71], v[66:67], v[70:71]
	v_cvt_pk_bf16_f32 v188, v76, v77
	v_cvt_pk_bf16_f32 v189, v78, v79
	v_cvt_pk_bf16_f32 v190, v68, v69
	v_cvt_pk_bf16_f32 v191, v70, v71
	global_store_dwordx4 v[234:235], v[188:191], off offset:2048 sc1
	v_pk_mul_f32 v[60:61], v[60:61], v[168:169] op_sel_hi:[1,0]
	v_pk_mul_f32 v[62:63], v[62:63], v[168:169] op_sel_hi:[1,0]
	v_pk_mul_f32 v[52:53], v[52:53], v[168:169] op_sel_hi:[1,0]
	v_pk_mul_f32 v[54:55], v[54:55], v[168:169] op_sel_hi:[1,0]
	v_pk_mul_f32 v[56:57], v[56:57], v[168:169] op_sel_hi:[1,0]
	v_pk_mul_f32 v[58:59], v[58:59], v[168:169] op_sel_hi:[1,0]
	v_pk_mul_f32 v[48:49], v[48:49], v[168:169] op_sel_hi:[1,0]
	v_pk_mul_f32 v[50:51], v[50:51], v[168:169] op_sel_hi:[1,0]
	v_pk_mul_f32 v[176:177], v[60:61], s[94:95]
	v_pk_mul_f32 v[178:179], v[62:63], s[94:95]
	v_pk_mul_f32 v[180:181], v[52:53], s[94:95]
	v_pk_mul_f32 v[182:183], v[54:55], s[94:95]
	v_exp_f32_e32 v176, v176
	v_exp_f32_e32 v177, v177
	v_exp_f32_e32 v178, v178
	v_exp_f32_e32 v179, v179
	v_exp_f32_e32 v180, v180
	v_exp_f32_e32 v181, v181
	v_exp_f32_e32 v182, v182
	v_exp_f32_e32 v183, v183
	v_pk_add_f32 v[176:177], v[176:177], 1.0 op_sel_hi:[1,0]
	v_pk_add_f32 v[178:179], v[178:179], 1.0 op_sel_hi:[1,0]
	v_pk_add_f32 v[180:181], v[180:181], 1.0 op_sel_hi:[1,0]
	v_pk_add_f32 v[182:183], v[182:183], 1.0 op_sel_hi:[1,0]
	v_rcp_f32_e32 v176, v176
	v_rcp_f32_e32 v177, v177
	v_rcp_f32_e32 v178, v178
	v_rcp_f32_e32 v179, v179
	v_rcp_f32_e32 v180, v180
	v_rcp_f32_e32 v181, v181
	v_rcp_f32_e32 v182, v182
	v_rcp_f32_e32 v183, v183
	v_pk_mul_f32 v[60:61], v[60:61], v[176:177]
	v_pk_mul_f32 v[62:63], v[62:63], v[178:179]
	v_pk_mul_f32 v[52:53], v[52:53], v[180:181]
	v_pk_mul_f32 v[54:55], v[54:55], v[182:183]
	v_pk_mul_f32 v[60:61], v[56:57], v[60:61]
	v_pk_mul_f32 v[62:63], v[58:59], v[62:63]
	v_pk_mul_f32 v[52:53], v[48:49], v[52:53]
	v_pk_mul_f32 v[54:55], v[50:51], v[54:55]
	v_cvt_pk_bf16_f32 v184, v60, v61
	v_cvt_pk_bf16_f32 v185, v62, v63
	v_cvt_pk_bf16_f32 v186, v52, v53
	v_cvt_pk_bf16_f32 v187, v54, v55
	global_store_dwordx4 v[236:237], v[184:187], off sc1
	v_pk_mul_f32 v[44:45], v[44:45], v[170:171] op_sel_hi:[1,0]
	v_pk_mul_f32 v[46:47], v[46:47], v[170:171] op_sel_hi:[1,0]
	v_pk_mul_f32 v[36:37], v[36:37], v[170:171] op_sel_hi:[1,0]
	v_pk_mul_f32 v[38:39], v[38:39], v[170:171] op_sel_hi:[1,0]
	v_pk_mul_f32 v[40:41], v[40:41], v[170:171] op_sel_hi:[1,0]
	v_pk_mul_f32 v[42:43], v[42:43], v[170:171] op_sel_hi:[1,0]
	v_pk_mul_f32 v[32:33], v[32:33], v[170:171] op_sel_hi:[1,0]
	v_pk_mul_f32 v[34:35], v[34:35], v[170:171] op_sel_hi:[1,0]
	v_pk_mul_f32 v[176:177], v[44:45], s[94:95]
	v_pk_mul_f32 v[178:179], v[46:47], s[94:95]
	v_pk_mul_f32 v[180:181], v[36:37], s[94:95]
	v_pk_mul_f32 v[182:183], v[38:39], s[94:95]
	v_exp_f32_e32 v176, v176
	v_exp_f32_e32 v177, v177
	v_exp_f32_e32 v178, v178
	v_exp_f32_e32 v179, v179
	v_exp_f32_e32 v180, v180
	v_exp_f32_e32 v181, v181
	v_exp_f32_e32 v182, v182
	v_exp_f32_e32 v183, v183
	v_pk_add_f32 v[176:177], v[176:177], 1.0 op_sel_hi:[1,0]
	v_pk_add_f32 v[178:179], v[178:179], 1.0 op_sel_hi:[1,0]
	v_pk_add_f32 v[180:181], v[180:181], 1.0 op_sel_hi:[1,0]
	v_pk_add_f32 v[182:183], v[182:183], 1.0 op_sel_hi:[1,0]
	v_rcp_f32_e32 v176, v176
	v_rcp_f32_e32 v177, v177
	v_rcp_f32_e32 v178, v178
	v_rcp_f32_e32 v179, v179
	v_rcp_f32_e32 v180, v180
	v_rcp_f32_e32 v181, v181
	v_rcp_f32_e32 v182, v182
	v_rcp_f32_e32 v183, v183
	v_pk_mul_f32 v[44:45], v[44:45], v[176:177]
	v_pk_mul_f32 v[46:47], v[46:47], v[178:179]
	v_pk_mul_f32 v[36:37], v[36:37], v[180:181]
	v_pk_mul_f32 v[38:39], v[38:39], v[182:183]
	v_pk_mul_f32 v[44:45], v[40:41], v[44:45]
	v_pk_mul_f32 v[46:47], v[42:43], v[46:47]
	v_pk_mul_f32 v[36:37], v[32:33], v[36:37]
	v_pk_mul_f32 v[38:39], v[34:35], v[38:39]
	v_cvt_pk_bf16_f32 v188, v44, v45
	v_cvt_pk_bf16_f32 v189, v46, v47
	v_cvt_pk_bf16_f32 v190, v36, v37
	v_cvt_pk_bf16_f32 v191, v38, v39
	global_store_dwordx4 v[236:237], v[188:191], off offset:2048 sc1
	v_pk_mul_f32 v[28:29], v[28:29], v[172:173] op_sel_hi:[1,0]
	v_pk_mul_f32 v[30:31], v[30:31], v[172:173] op_sel_hi:[1,0]
	v_pk_mul_f32 v[20:21], v[20:21], v[172:173] op_sel_hi:[1,0]
	v_pk_mul_f32 v[22:23], v[22:23], v[172:173] op_sel_hi:[1,0]
	v_pk_mul_f32 v[24:25], v[24:25], v[172:173] op_sel_hi:[1,0]
	v_pk_mul_f32 v[26:27], v[26:27], v[172:173] op_sel_hi:[1,0]
	v_pk_mul_f32 v[16:17], v[16:17], v[172:173] op_sel_hi:[1,0]
	v_pk_mul_f32 v[18:19], v[18:19], v[172:173] op_sel_hi:[1,0]
	v_pk_mul_f32 v[176:177], v[28:29], s[94:95]
	v_pk_mul_f32 v[178:179], v[30:31], s[94:95]
	v_pk_mul_f32 v[180:181], v[20:21], s[94:95]
	v_pk_mul_f32 v[182:183], v[22:23], s[94:95]
	v_exp_f32_e32 v176, v176
	v_exp_f32_e32 v177, v177
	v_exp_f32_e32 v178, v178
	v_exp_f32_e32 v179, v179
	v_exp_f32_e32 v180, v180
	v_exp_f32_e32 v181, v181
	v_exp_f32_e32 v182, v182
	v_exp_f32_e32 v183, v183
	v_pk_add_f32 v[176:177], v[176:177], 1.0 op_sel_hi:[1,0]
	v_pk_add_f32 v[178:179], v[178:179], 1.0 op_sel_hi:[1,0]
	v_pk_add_f32 v[180:181], v[180:181], 1.0 op_sel_hi:[1,0]
	v_pk_add_f32 v[182:183], v[182:183], 1.0 op_sel_hi:[1,0]
	v_rcp_f32_e32 v176, v176
	v_rcp_f32_e32 v177, v177
	v_rcp_f32_e32 v178, v178
	v_rcp_f32_e32 v179, v179
	v_rcp_f32_e32 v180, v180
	v_rcp_f32_e32 v181, v181
	v_rcp_f32_e32 v182, v182
	v_rcp_f32_e32 v183, v183
	v_pk_mul_f32 v[28:29], v[28:29], v[176:177]
	v_pk_mul_f32 v[30:31], v[30:31], v[178:179]
	v_pk_mul_f32 v[20:21], v[20:21], v[180:181]
	v_pk_mul_f32 v[22:23], v[22:23], v[182:183]
	v_pk_mul_f32 v[28:29], v[24:25], v[28:29]
	v_pk_mul_f32 v[30:31], v[26:27], v[30:31]
	v_pk_mul_f32 v[20:21], v[16:17], v[20:21]
	v_pk_mul_f32 v[22:23], v[18:19], v[22:23]
	v_cvt_pk_bf16_f32 v184, v28, v29
	v_cvt_pk_bf16_f32 v185, v30, v31
	v_cvt_pk_bf16_f32 v186, v20, v21
	v_cvt_pk_bf16_f32 v187, v22, v23
	global_store_dwordx4 v[238:239], v[184:187], off sc1
	v_pk_mul_f32 v[12:13], v[12:13], v[174:175] op_sel_hi:[1,0]
	v_pk_mul_f32 v[14:15], v[14:15], v[174:175] op_sel_hi:[1,0]
	v_pk_mul_f32 v[4:5], v[4:5], v[174:175] op_sel_hi:[1,0]
	v_pk_mul_f32 v[6:7], v[6:7], v[174:175] op_sel_hi:[1,0]
	v_pk_mul_f32 v[8:9], v[8:9], v[174:175] op_sel_hi:[1,0]
	v_pk_mul_f32 v[10:11], v[10:11], v[174:175] op_sel_hi:[1,0]
	v_pk_mul_f32 v[0:1], v[0:1], v[174:175] op_sel_hi:[1,0]
	v_pk_mul_f32 v[2:3], v[2:3], v[174:175] op_sel_hi:[1,0]
	v_pk_mul_f32 v[176:177], v[12:13], s[94:95]
	v_pk_mul_f32 v[178:179], v[14:15], s[94:95]
	v_pk_mul_f32 v[180:181], v[4:5], s[94:95]
	v_pk_mul_f32 v[182:183], v[6:7], s[94:95]
	v_exp_f32_e32 v176, v176
	v_exp_f32_e32 v177, v177
	v_exp_f32_e32 v178, v178
	v_exp_f32_e32 v179, v179
	v_exp_f32_e32 v180, v180
	v_exp_f32_e32 v181, v181
	v_exp_f32_e32 v182, v182
	v_exp_f32_e32 v183, v183
	v_pk_add_f32 v[176:177], v[176:177], 1.0 op_sel_hi:[1,0]
	v_pk_add_f32 v[178:179], v[178:179], 1.0 op_sel_hi:[1,0]
	v_pk_add_f32 v[180:181], v[180:181], 1.0 op_sel_hi:[1,0]
	v_pk_add_f32 v[182:183], v[182:183], 1.0 op_sel_hi:[1,0]
	v_rcp_f32_e32 v176, v176
	v_rcp_f32_e32 v177, v177
	v_rcp_f32_e32 v178, v178
	v_rcp_f32_e32 v179, v179
	v_rcp_f32_e32 v180, v180
	v_rcp_f32_e32 v181, v181
	v_rcp_f32_e32 v182, v182
	v_rcp_f32_e32 v183, v183
	v_pk_mul_f32 v[12:13], v[12:13], v[176:177]
	v_pk_mul_f32 v[14:15], v[14:15], v[178:179]
	v_pk_mul_f32 v[4:5], v[4:5], v[180:181]
	v_pk_mul_f32 v[6:7], v[6:7], v[182:183]
	v_pk_mul_f32 v[12:13], v[8:9], v[12:13]
	v_pk_mul_f32 v[14:15], v[10:11], v[14:15]
	v_pk_mul_f32 v[4:5], v[0:1], v[4:5]
	v_pk_mul_f32 v[6:7], v[2:3], v[6:7]
	v_cvt_pk_bf16_f32 v188, v12, v13
	v_cvt_pk_bf16_f32 v189, v14, v15
	v_cvt_pk_bf16_f32 v190, v4, v5
	v_cvt_pk_bf16_f32 v191, v6, v7
	global_store_dwordx4 v[238:239], v[188:191], off offset:2048 sc1
	s_andn2_b64 vcc, exec, s[4:5]
	s_mov_b64 s[4:5], -1
	s_cbranch_vccnz .LBB0_1333
	s_andn2_b64 vcc, exec, s[6:7]
	s_cbranch_vccnz .LBB0_1332
	s_barrier
	s_branch .LBB0_1332
